# lag waves pre-issue the first two V^T fragments of their next MFMA half during the softmax half (registers freed by LDS-DMA)
# baseline (speedup 1.0000x reference)
.LBB0_227:
	s_lshl_b32 s4, s59, 11
	s_and_b32 s5, s4, 0x1000000
	s_lshl_b32 s4, s36, 4
	s_and_b32 s28, s4, 0x700
	v_lshl_or_b32 v96, v148, 1, s28
	v_or_b32_e32 v96, s5, v96
	v_mov_b32_e32 v97, v209
	s_lshl_b32 s21, s21, 9
	s_mov_b32 s65, 2
	s_add_i32 s66, s8, 2
	s_mov_b32 s4, 1
	v_lshl_add_u64 v[174:175], v[170:171], 0, v[96:97]
	v_subrev_u32_e32 v204, s21, v194
	s_add_i32 s33, s61, s8
	s_mov_b32 s87, 0
	s_movk_i32 s68, 0xff00
	s_waitcnt lgkmcnt(0)
	s_barrier
	s_and_b64 vcc, exec, s[16:17]
	s_cbranch_vccz .Latt_p_qk
	s_mul_i32 s29, s87, 0x5000
	v_add_u32_e32 v133, s29, v165
	ds_read_b64_tr_b16 v[136:137], v133 offset:34816
	ds_read_b64_tr_b16 v[138:139], v133 offset:37376
	ds_read_b64_tr_b16 v[140:141], v133 offset:39936
	ds_read_b64_tr_b16 v[142:143], v133 offset:42496
	s_cmp_ge_u32 s65, s66
	s_cbranch_scc1 .LBB0_228
	s_mov_b32 s5, 0
	s_mov_b32 s28, 0x12800
	s_add_i32 m0, s5, s32
	s_nop 0
	global_load_lds_dwordx4 v128, s[80:81]
	s_add_i32 m0, m0, 0x2000
	s_nop 0
	global_load_lds_dwordx4 v129, s[80:81]
	s_cmp_eq_u32 s56, 0
	s_cbranch_scc0 .Ldk_p3
	s_add_i32 m0, s5, 0x4000
	s_nop 0
	global_load_lds_dwordx4 v132, s[80:81]

.Latt_a:
	s_mul_i32 s4, s87, 0x5000
	v_add_u32_e32 v205, s4, v165
	v_add_u32_e32 v206, s5, v192
	s_waitcnt lgkmcnt(0)
	ds_read_b64_tr_b16 v[96:97], v205 offset:45056
	ds_read_b64_tr_b16 v[98:99], v205 offset:47616
	ds_read_b64_tr_b16 v[100:101], v205 offset:50176
	ds_read_b64_tr_b16 v[102:103], v205 offset:52736
	ds_read_b64_tr_b16 v[104:105], v205 offset:34880
	ds_read_b64_tr_b16 v[106:107], v205 offset:37440
	ds_read_b64_tr_b16 v[108:109], v205 offset:40000
	ds_read_b64_tr_b16 v[110:111], v205 offset:42560
	ds_read_b64_tr_b16 v[176:177], v205 offset:45120
	ds_read_b64_tr_b16 v[178:179], v205 offset:47680
	ds_read_b64_tr_b16 v[180:181], v205 offset:50240
	ds_read_b64_tr_b16 v[182:183], v205 offset:52800
	ds_read_b64_tr_b16 v[184:185], v205 offset:34944
	ds_read_b64_tr_b16 v[186:187], v205 offset:37504
	s_setprio 1
	v_mfma_f32_32x32x16_bf16 v[32:47], v[136:139], v[80:83], v[32:47]
	v_mfma_f32_32x32x16_bf16 v[32:47], v[140:143], v[84:87], v[32:47]
	s_waitcnt lgkmcnt(12)
	v_mfma_f32_32x32x16_bf16 v[32:47], v[96:99], v[88:91], v[32:47]
	ds_read_b64_tr_b16 v[136:137], v205 offset:40064
	ds_read_b64_tr_b16 v[138:139], v205 offset:42624
	s_waitcnt lgkmcnt(12)
	v_mfma_f32_32x32x16_bf16 v[32:47], v[100:103], v[92:95], v[32:47]
	ds_read_b64_tr_b16 v[140:141], v205 offset:45184
	ds_read_b64_tr_b16 v[142:143], v205 offset:47744
	s_waitcnt lgkmcnt(12)
	v_mfma_f32_32x32x16_bf16 v[16:31], v[104:107], v[80:83], v[16:31]
	ds_read_b64_tr_b16 v[96:97], v205 offset:50304
	ds_read_b64_tr_b16 v[98:99], v205 offset:52864
	s_waitcnt lgkmcnt(12)
	v_mfma_f32_32x32x16_bf16 v[16:31], v[108:111], v[84:87], v[16:31]
	ds_read_b64_tr_b16 v[100:101], v205 offset:35008
	ds_read_b64_tr_b16 v[102:103], v205 offset:37568
	s_waitcnt lgkmcnt(12)
	v_mfma_f32_32x32x16_bf16 v[16:31], v[176:179], v[88:91], v[16:31]
	ds_read_b64_tr_b16 v[104:105], v205 offset:40128
	ds_read_b64_tr_b16 v[106:107], v205 offset:42688
	s_waitcnt lgkmcnt(12)
	v_mfma_f32_32x32x16_bf16 v[16:31], v[180:183], v[92:95], v[16:31]
	ds_read_b64_tr_b16 v[108:109], v205 offset:45248
	ds_read_b64_tr_b16 v[110:111], v205 offset:47808
	s_waitcnt lgkmcnt(12)
	v_mfma_f32_32x32x16_bf16 v[0:15], v[184:187], v[80:83], v[0:15]
	ds_read_b64_tr_b16 v[176:177], v205 offset:50368
	ds_read_b64_tr_b16 v[178:179], v205 offset:52928
	s_waitcnt lgkmcnt(12)
	v_mfma_f32_32x32x16_bf16 v[0:15], v[136:139], v[84:87], v[0:15]
	ds_read_b128 v[210:213], v206 offset:8704
	ds_read_b128 v[180:183], v206 offset:8736
	s_waitcnt lgkmcnt(12)
	v_mfma_f32_32x32x16_bf16 v[0:15], v[140:143], v[88:91], v[0:15]
	ds_read_b128 v[184:187], v206 offset:8768
	ds_read_b128 v[188:191], v206
	s_waitcnt lgkmcnt(12)
	v_mfma_f32_32x32x16_bf16 v[0:15], v[96:99], v[92:95], v[0:15]
	ds_read_b128 v[136:139], v206 offset:8800
	ds_read_b128 v[224:227], v206 offset:32
	s_waitcnt lgkmcnt(12)
	v_mfma_f32_32x32x16_bf16 v[48:63], v[100:103], v[80:83], v[48:63]
	ds_read_b128 v[228:231], v206 offset:64
	ds_read_b128 v[248:251], v206 offset:96
	s_waitcnt lgkmcnt(12)
	v_mfma_f32_32x32x16_bf16 v[48:63], v[104:107], v[84:87], v[48:63]
	s_waitcnt lgkmcnt(10)
	v_mfma_f32_32x32x16_bf16 v[48:63], v[108:111], v[88:91], v[48:63]
	s_waitcnt lgkmcnt(8)
	v_mfma_f32_32x32x16_bf16 v[48:63], v[176:179], v[92:95], v[48:63]
	s_waitcnt lgkmcnt(7)
	v_mfma_f32_32x32x16_bf16 v[80:95], v[210:213], v[112:115], v[64:79]
	s_waitcnt lgkmcnt(6)
	v_mfma_f32_32x32x16_bf16 v[80:95], v[180:183], v[116:119], v[80:95]
	s_waitcnt lgkmcnt(5)
	v_mfma_f32_32x32x16_bf16 v[80:95], v[184:187], v[120:123], v[80:95]
	s_waitcnt lgkmcnt(3)
	v_mfma_f32_32x32x16_bf16 v[80:95], v[136:139], v[124:127], v[80:95]
	s_waitcnt lgkmcnt(4)
	v_mfma_f32_32x32x16_bf16 v[96:111], v[188:191], v[112:115], v[64:79]
	s_waitcnt lgkmcnt(2)
	v_mfma_f32_32x32x16_bf16 v[96:111], v[224:227], v[116:119], v[96:111]
	s_waitcnt lgkmcnt(1)
	v_mfma_f32_32x32x16_bf16 v[96:111], v[228:231], v[120:123], v[96:111]
	s_waitcnt lgkmcnt(0)
	v_mfma_f32_32x32x16_bf16 v[96:111], v[248:251], v[124:127], v[96:111]
	s_setprio 0
	s_cmp_gt_i32 s33, 2
	s_cbranch_scc1 .Latt_a_stg
	s_waitcnt lgkmcnt(0)
	v_add_u32_e32 v205, s68, v204
	v_add_u32_e32 v176, 0x17d00, v205
	v_add_u32_e32 v178, 0x17d80, v205
	ds_read2_b32 v[176:177], v176 offset1:1
	ds_read2_b32 v[178:179], v178 offset1:1
	v_add_u32_e32 v180, 0x17d08, v205
	v_add_u32_e32 v182, 0x17d88, v205
	v_add_u32_e32 v184, 0x17d20, v205
	v_add_u32_e32 v186, 0x17da0, v205
	v_add_u32_e32 v188, 0x17d28, v205
	v_add_u32_e32 v190, 0x17da8, v205
	v_add_u32_e32 v206, 0x17d40, v205
	v_add_u32_e32 v210, 0x17dc0, v205
	v_add_u32_e32 v212, 0x17d48, v205
	v_add_u32_e32 v221, 0x17dc8, v205
	ds_read2_b32 v[180:181], v180 offset1:1
	ds_read2_b32 v[182:183], v182 offset1:1
	ds_read2_b32 v[184:185], v184 offset1:1
	ds_read2_b32 v[186:187], v186 offset1:1
	ds_read2_b32 v[188:189], v188 offset1:1
	ds_read2_b32 v[190:191], v190 offset1:1
	ds_read2_b32 v[206:207], v206 offset1:1
	ds_read2_b32 v[210:211], v210 offset1:1
	ds_read2_b32 v[212:213], v212 offset1:1
	ds_read2_b32 v[224:225], v221 offset1:1
	v_add_u32_e32 v221, 0x17d60, v205
	v_add_u32_e32 v223, 0x17de0, v205
	ds_read2_b32 v[226:227], v221 offset1:1
	ds_read2_b32 v[228:229], v223 offset1:1
	v_add_u32_e32 v221, 0x17d68, v205
	v_add_u32_e32 v205, 0x17de8, v205
	ds_read2_b32 v[230:231], v221 offset1:1
	s_waitcnt lgkmcnt(14)
	v_pk_add_f32 v[96:97], v[96:97], v[176:177]
	ds_read2_b32 v[176:177], v205 offset1:1
	s_waitcnt lgkmcnt(3)
	v_pk_add_f32 v[108:109], v[108:109], v[226:227]
	v_pk_add_f32 v[106:107], v[106:107], v[212:213]
	s_waitcnt lgkmcnt(1)
	v_pk_add_f32 v[110:111], v[110:111], v[230:231]
	v_pk_add_f32 v[104:105], v[104:105], v[206:207]
	v_pk_add_f32 v[102:103], v[102:103], v[188:189]
	v_pk_add_f32 v[100:101], v[100:101], v[184:185]
	v_pk_add_f32 v[98:99], v[98:99], v[180:181]
	s_waitcnt lgkmcnt(0)
	v_pk_add_f32 v[94:95], v[94:95], v[176:177]
	v_pk_add_f32 v[92:93], v[92:93], v[228:229]
	v_pk_add_f32 v[90:91], v[90:91], v[224:225]
	v_pk_add_f32 v[88:89], v[88:89], v[210:211]
	v_pk_add_f32 v[86:87], v[86:87], v[190:191]
	v_pk_add_f32 v[84:85], v[84:85], v[186:187]
	v_pk_add_f32 v[82:83], v[82:83], v[182:183]
	v_pk_add_f32 v[80:81], v[80:81], v[178:179]
	s_nop 0

.Latt_a_nod:
	s_mul_i32 s4, s69, 0x5000
	v_add_u32_e32 v133, s4, v165
	ds_read_b64_tr_b16 v[136:137], v133 offset:34816
	ds_read_b64_tr_b16 v[138:139], v133 offset:37376
	ds_read_b64_tr_b16 v[140:141], v133 offset:39936
	ds_read_b64_tr_b16 v[142:143], v133 offset:42496
	s_nop 9
	v_max_f32_e32 v176, v96, v80
	v_max3_f32 v177, v81, v98, v82
	v_max3_f32 v176, v176, v97, v99
	v_max3_f32 v177, v177, v100, v84
	v_max3_f32 v176, v176, v83, v101
	v_max3_f32 v177, v177, v102, v86
	v_max3_f32 v176, v176, v85, v103
	v_max3_f32 v177, v177, v104, v88
	v_max3_f32 v176, v176, v87, v105
	v_max3_f32 v177, v177, v106, v90
	v_max3_f32 v176, v176, v89, v107
	v_max3_f32 v177, v177, v108, v92
	v_max3_f32 v176, v176, v91, v109
	v_max3_f32 v177, v177, v110, v94
	v_max3_f32 v176, v176, v93, v111
	v_max3_f32 v176, v176, v95, v177
	v_mov_b32_e32 v177, v176
	s_nop 1
	v_permlane32_swap_b32_e32 v176, v177
	v_max_f32_e32 v176, v176, v177
	s_mov_b32 s4, 0x41000000
	v_cmp_lt_f32_e32 vcc, s4, v176
	s_cbranch_vccz .Latt_a_exp
	v_max_f32_e32 v64, v176, v176
	v_max_f32_e32 v66, 0, v64
	v_exp_f32_e64 v176, -v66
	v_add_f32_e32 v173, v173, v66
	v_xor_b32_e32 v64, 0x80000000, v173
	v_pk_add_f32 v[96:97], v[96:97], v[66:67] op_sel_hi:[1,0] neg_lo:[0,1] neg_hi:[0,1]
	v_pk_add_f32 v[80:81], v[80:81], v[66:67] op_sel_hi:[1,0] neg_lo:[0,1] neg_hi:[0,1]
	v_pk_add_f32 v[98:99], v[98:99], v[66:67] op_sel_hi:[1,0] neg_lo:[0,1] neg_hi:[0,1]
	v_pk_add_f32 v[82:83], v[82:83], v[66:67] op_sel_hi:[1,0] neg_lo:[0,1] neg_hi:[0,1]
	v_pk_add_f32 v[100:101], v[100:101], v[66:67] op_sel_hi:[1,0] neg_lo:[0,1] neg_hi:[0,1]
	v_pk_add_f32 v[84:85], v[84:85], v[66:67] op_sel_hi:[1,0] neg_lo:[0,1] neg_hi:[0,1]
	v_pk_add_f32 v[102:103], v[102:103], v[66:67] op_sel_hi:[1,0] neg_lo:[0,1] neg_hi:[0,1]
	v_pk_add_f32 v[86:87], v[86:87], v[66:67] op_sel_hi:[1,0] neg_lo:[0,1] neg_hi:[0,1]
	v_pk_add_f32 v[104:105], v[104:105], v[66:67] op_sel_hi:[1,0] neg_lo:[0,1] neg_hi:[0,1]
	v_pk_add_f32 v[88:89], v[88:89], v[66:67] op_sel_hi:[1,0] neg_lo:[0,1] neg_hi:[0,1]
	v_pk_add_f32 v[106:107], v[106:107], v[66:67] op_sel_hi:[1,0] neg_lo:[0,1] neg_hi:[0,1]
	v_pk_add_f32 v[90:91], v[90:91], v[66:67] op_sel_hi:[1,0] neg_lo:[0,1] neg_hi:[0,1]
	v_pk_add_f32 v[108:109], v[108:109], v[66:67] op_sel_hi:[1,0] neg_lo:[0,1] neg_hi:[0,1]
	v_pk_add_f32 v[92:93], v[92:93], v[66:67] op_sel_hi:[1,0] neg_lo:[0,1] neg_hi:[0,1]
	v_pk_add_f32 v[110:111], v[110:111], v[66:67] op_sel_hi:[1,0] neg_lo:[0,1] neg_hi:[0,1]
	v_pk_add_f32 v[94:95], v[94:95], v[66:67] op_sel_hi:[1,0] neg_lo:[0,1] neg_hi:[0,1]
	v_mov_b32_e32 v65, v64
	v_mov_b32_e32 v66, v64
	v_mov_b32_e32 v67, v64
	v_mov_b32_e32 v68, v64
	v_mov_b32_e32 v69, v64
	v_mov_b32_e32 v70, v64
	v_mov_b32_e32 v71, v64
	v_mov_b32_e32 v72, v64
	v_mov_b32_e32 v73, v64
	v_mov_b32_e32 v74, v64
	v_mov_b32_e32 v75, v64
	v_mov_b32_e32 v76, v64
	v_mov_b32_e32 v77, v64
	v_mov_b32_e32 v78, v64
	v_mov_b32_e32 v79, v64
	v_pk_mul_f32 v[46:47], v[46:47], v[176:177] op_sel_hi:[1,0]
	v_pk_mul_f32 v[44:45], v[44:45], v[176:177] op_sel_hi:[1,0]
	v_pk_mul_f32 v[42:43], v[42:43], v[176:177] op_sel_hi:[1,0]
	v_pk_mul_f32 v[40:41], v[40:41], v[176:177] op_sel_hi:[1,0]
	v_pk_mul_f32 v[38:39], v[38:39], v[176:177] op_sel_hi:[1,0]
	v_pk_mul_f32 v[36:37], v[36:37], v[176:177] op_sel_hi:[1,0]
	v_pk_mul_f32 v[34:35], v[34:35], v[176:177] op_sel_hi:[1,0]
	v_pk_mul_f32 v[32:33], v[32:33], v[176:177] op_sel_hi:[1,0]
	v_pk_mul_f32 v[30:31], v[30:31], v[176:177] op_sel_hi:[1,0]
	v_pk_mul_f32 v[28:29], v[28:29], v[176:177] op_sel_hi:[1,0]
	v_pk_mul_f32 v[26:27], v[26:27], v[176:177] op_sel_hi:[1,0]
	v_pk_mul_f32 v[24:25], v[24:25], v[176:177] op_sel_hi:[1,0]
	v_pk_mul_f32 v[22:23], v[22:23], v[176:177] op_sel_hi:[1,0]
	v_pk_mul_f32 v[20:21], v[20:21], v[176:177] op_sel_hi:[1,0]
	v_pk_mul_f32 v[18:19], v[18:19], v[176:177] op_sel_hi:[1,0]
	v_pk_mul_f32 v[16:17], v[16:17], v[176:177] op_sel_hi:[1,0]
	v_pk_mul_f32 v[14:15], v[14:15], v[176:177] op_sel_hi:[1,0]
	v_pk_mul_f32 v[12:13], v[12:13], v[176:177] op_sel_hi:[1,0]
	v_pk_mul_f32 v[10:11], v[10:11], v[176:177] op_sel_hi:[1,0]
	v_pk_mul_f32 v[8:9], v[8:9], v[176:177] op_sel_hi:[1,0]
	v_pk_mul_f32 v[6:7], v[6:7], v[176:177] op_sel_hi:[1,0]
	v_pk_mul_f32 v[4:5], v[4:5], v[176:177] op_sel_hi:[1,0]
	v_pk_mul_f32 v[2:3], v[2:3], v[176:177] op_sel_hi:[1,0]
	v_pk_mul_f32 v[0:1], v[0:1], v[176:177] op_sel_hi:[1,0]
	v_pk_mul_f32 v[62:63], v[62:63], v[176:177] op_sel_hi:[1,0]
	v_pk_mul_f32 v[60:61], v[60:61], v[176:177] op_sel_hi:[1,0]
	v_pk_mul_f32 v[58:59], v[58:59], v[176:177] op_sel_hi:[1,0]
	v_pk_mul_f32 v[56:57], v[56:57], v[176:177] op_sel_hi:[1,0]
	v_pk_mul_f32 v[54:55], v[54:55], v[176:177] op_sel_hi:[1,0]
	v_pk_mul_f32 v[52:53], v[52:53], v[176:177] op_sel_hi:[1,0]
	v_pk_mul_f32 v[50:51], v[50:51], v[176:177] op_sel_hi:[1,0]
	v_pk_mul_f32 v[48:49], v[48:49], v[176:177] op_sel_hi:[1,0]
	v_mul_f32_e32 v172, v172, v176
